# P6: the third act items are spread over all 256 workgroups (7 waves each) instead of 3 items on every wave of the first 214 workgroups
# speedup vs baseline: 1.0059x; 1.0059x over previous
; __global__ void __launch_bounds__(512, 2) fwd_kernel(Args args) {
;     ...
;         for (int it = gw; it < 264 * 22; it += NGW) act_item(it, UP, HALO, args.in[I_SCONV], args.in[I_WCONV], args.in[I_BCONV], out, lane);
.LBB0_770:
	s_add_i32 s80, s80, s96
	s_cmpk_gt_i32 s80, 0x17ff
	s_cbranch_scc1 .LBB0_819
	v_add_u32_e32 v43, s70, v43
	s_cmpk_lt_i32 s80, 0x1000
	s_cbranch_scc1 .LBB0_771
	v_readlane_b32 s0, v237, 12
	s_mul_i32 s1, s2, 7
	s_nop 0
	s_cmp_gt_u32 s0, 6
	s_cbranch_scc1 .LBB0_819
	s_add_i32 s1, s1, s0
	s_addk_i32 s1, 0x1000
	s_cmpk_gt_i32 s1, 0x16af
	s_cbranch_scc1 .LBB0_819
	s_sub_i32 s0, s1, s80
	s_lshl_b32 s0, s0, 7
	v_add_u32_e32 v43, s0, v43
	s_mov_b32 s80, s1
